# hand-written EpiResid epilogue: residual loads 4 row-groups ahead, batched row-sum reductions
# baseline (speedup 1.0000x reference)
; __device__ __forceinline__ unsigned cvt_pk_bf16(float lo, float hi) { unsigned r; asm volatile("v_cvt_pk_bf16_f32 %0, %1, %2" : "=v"(r) : "v"(lo), "v"(hi)); return r; }
;     __device__ __forceinline__ void operator()(const f32x4 (&acc)[2][2][4][2], const Unit& u, int wr, int wc, int fr, int fq) const {
;         const int row0 = u.pm * BM + wr * 64 + fr, col0 = u.pn * BM + wc * 32 + 4 * fq;
;         f32x4 bs[2][4];
; #pragma unroll
;         for (int q = 0; q < 4; ++q) bs[0][q] = *(const f32x4*)(xin + (size_t)row0 * ldc + col0 + (q >> 1) * HALF + (q & 1) * 16);
; #pragma unroll
;         for (int gi = 0; gi < 8; ++gi) {
;             const int ai = gi >> 2, m = gi & 3;
;             const int row = row0 + ai * HALF + m * 16;
;             const size_t off = (size_t)row * ldc + col0;
;             if (gi + 1 < 8) {
;                 const size_t offn = (size_t)(row0 + ((gi + 1) >> 2) * HALF + ((gi + 1) & 3) * 16) * ldc + col0;
; #pragma unroll
;                 for (int q = 0; q < 4; ++q) bs[(gi + 1) & 1][q] = *(const f32x4*)(xin + offn + (q >> 1) * HALF + (q & 1) * 16);
;             }
;             float sq = 0.f;
; #pragma unroll
;             for (int q = 0; q < 4; ++q) {
;                 const int bj = q >> 1, n = q & 1;
;                 const f32x4 o = bs[gi & 1][q] + acc[ai][bj][m][n];
;                 *(f32x4*)(out + off + bj * HALF + n * 16) = o;
;                 if (ss) {
;                     u32x2 w; w.x = cvt_pk_bf16(o[0], o[1]); w.y = cvt_pk_bf16(o[2], o[3]);
;                     *(u32x2*)(xb + off + bj * HALF + n * 16) = w;
;                     sq += (o[0] * o[0] + o[1] * o[1]) + (o[2] * o[2] + o[3] * o[3]);
;                 }
;             }
;             if (ss) { sq += __shfl_xor(sq, 16); sq += __shfl_xor(sq, 32); if (fq == 0) ss[(size_t)row * 32 + u.pn * 4 + wc] = sq; }
.LBB0_345:
	s_andn2_b64 vcc, exec, s[26:27]
	s_cbranch_vccnz .Lres_noss
	v_lshl_add_u32 v246, s55, 8, v188
	v_lshl_or_b32 v247, s2, 8, v190
	v_lshlrev_b32_e32 v247, 2, v247
	v_lshl_add_u32 v160, v246, 13, v247
	v_add_u32_e32 v161, 0x20000, v160
	v_add_u32_e32 v162, 0x40000, v160
	v_add_u32_e32 v163, 0x60000, v160
	v_add_u32_e32 v164, 0x100000, v160
	v_add_u32_e32 v165, 0x120000, v160
	v_add_u32_e32 v192, 0x140000, v160
	v_add_u32_e32 v193, 0x160000, v160
	global_load_dwordx4 v[128:131], v160, s[14:15]
	global_load_dwordx4 v[132:135], v160, s[14:15] offset:64
	global_load_dwordx4 v[136:139], v160, s[14:15] offset:512
	global_load_dwordx4 v[140:143], v160, s[14:15] offset:576
	global_load_dwordx4 v[144:147], v161, s[14:15]
	global_load_dwordx4 v[148:151], v161, s[14:15] offset:64
	global_load_dwordx4 v[152:155], v161, s[14:15] offset:512
	global_load_dwordx4 v[156:159], v161, s[14:15] offset:576
	global_load_dwordx4 v[206:209], v162, s[14:15]
	global_load_dwordx4 v[210:213], v162, s[14:15] offset:64
	global_load_dwordx4 v[214:217], v162, s[14:15] offset:512
	global_load_dwordx4 v[218:221], v162, s[14:15] offset:576
	global_load_dwordx4 v[222:225], v163, s[14:15]
	global_load_dwordx4 v[226:229], v163, s[14:15] offset:64
	global_load_dwordx4 v[230:233], v163, s[14:15] offset:512
	global_load_dwordx4 v[234:237], v163, s[14:15] offset:576
	s_lshl_b32 s34, s2, 4
	s_lshl_b32 s35, s46, 2
	s_add_i32 s34, s34, s35
	v_lshl_add_u32 v246, v246, 7, s34
	v_mov_b32_e32 v189, v246
	s_waitcnt vmcnt(12)
	v_pk_add_f32 v[124:125], v[128:129], v[124:125]
	v_pk_add_f32 v[126:127], v[130:131], v[126:127]
	v_pk_add_f32 v[120:121], v[132:133], v[120:121]
	v_pk_add_f32 v[122:123], v[134:135], v[122:123]
	v_pk_add_f32 v[116:117], v[136:137], v[116:117]
	v_pk_add_f32 v[118:119], v[138:139], v[118:119]
	v_pk_add_f32 v[108:109], v[140:141], v[108:109]
	v_pk_add_f32 v[110:111], v[142:143], v[110:111]
	global_load_dwordx4 v[128:131], v164, s[14:15]
	global_load_dwordx4 v[132:135], v164, s[14:15] offset:64
	global_load_dwordx4 v[136:139], v164, s[14:15] offset:512
	global_load_dwordx4 v[140:143], v164, s[14:15] offset:576
	global_store_dwordx4 v160, v[124:127], s[72:73]
	global_store_dwordx4 v160, v[120:123], s[72:73] offset:64
	global_store_dwordx4 v160, v[116:119], s[72:73] offset:512
	global_store_dwordx4 v160, v[108:111], s[72:73] offset:576
	v_lshrrev_b32_e32 v245, 1, v160
	v_cvt_pk_bf16_f32 v194, v124, v125
	v_cvt_pk_bf16_f32 v195, v126, v127
	v_mul_f32_e32 v246, v125, v125
	v_mul_f32_e32 v247, v127, v127
	global_store_dwordx2 v245, v[194:195], s[22:23]
	v_fmac_f32_e32 v246, v124, v124
	v_fmac_f32_e32 v247, v126, v126
	v_add_f32_e32 v180, v246, v247
	v_cvt_pk_bf16_f32 v196, v120, v121
	v_cvt_pk_bf16_f32 v197, v122, v123
	v_mul_f32_e32 v246, v121, v121
	v_mul_f32_e32 v247, v123, v123
	global_store_dwordx2 v245, v[196:197], s[22:23] offset:32
	v_fmac_f32_e32 v246, v120, v120
	v_fmac_f32_e32 v247, v122, v122
	v_add_f32_e32 v246, v246, v247
	v_add_f32_e32 v180, v246, v180
	v_cvt_pk_bf16_f32 v194, v116, v117
	v_cvt_pk_bf16_f32 v195, v118, v119
	v_mul_f32_e32 v246, v117, v117
	v_mul_f32_e32 v247, v119, v119
	global_store_dwordx2 v245, v[194:195], s[22:23] offset:256
	v_fmac_f32_e32 v246, v116, v116
	v_fmac_f32_e32 v247, v118, v118
	v_add_f32_e32 v246, v246, v247
	v_add_f32_e32 v180, v246, v180
	v_cvt_pk_bf16_f32 v196, v108, v109
	v_cvt_pk_bf16_f32 v197, v110, v111
	v_mul_f32_e32 v246, v109, v109
	v_mul_f32_e32 v247, v111, v111
	global_store_dwordx2 v245, v[196:197], s[22:23] offset:288
	v_fmac_f32_e32 v246, v108, v108
	v_fmac_f32_e32 v247, v110, v110
	v_add_f32_e32 v246, v246, v247
	v_add_f32_e32 v180, v246, v180
	s_waitcnt vmcnt(20)
	v_pk_add_f32 v[112:113], v[144:145], v[112:113]
	v_pk_add_f32 v[114:115], v[146:147], v[114:115]
	v_pk_add_f32 v[104:105], v[148:149], v[104:105]
	v_pk_add_f32 v[106:107], v[150:151], v[106:107]
	v_pk_add_f32 v[100:101], v[152:153], v[100:101]
	v_pk_add_f32 v[102:103], v[154:155], v[102:103]
	v_pk_add_f32 v[92:93], v[156:157], v[92:93]
	v_pk_add_f32 v[94:95], v[158:159], v[94:95]
	global_load_dwordx4 v[144:147], v165, s[14:15]
	global_load_dwordx4 v[148:151], v165, s[14:15] offset:64
	global_load_dwordx4 v[152:155], v165, s[14:15] offset:512
	global_load_dwordx4 v[156:159], v165, s[14:15] offset:576
	global_store_dwordx4 v161, v[112:115], s[72:73]
	global_store_dwordx4 v161, v[104:107], s[72:73] offset:64
	global_store_dwordx4 v161, v[100:103], s[72:73] offset:512
	global_store_dwordx4 v161, v[92:95], s[72:73] offset:576
	v_lshrrev_b32_e32 v245, 1, v161
	v_cvt_pk_bf16_f32 v194, v112, v113
	v_cvt_pk_bf16_f32 v195, v114, v115
	v_mul_f32_e32 v246, v113, v113
	v_mul_f32_e32 v247, v115, v115
	global_store_dwordx2 v245, v[194:195], s[22:23]
	v_fmac_f32_e32 v246, v112, v112
	v_fmac_f32_e32 v247, v114, v114
	v_add_f32_e32 v181, v246, v247
	v_cvt_pk_bf16_f32 v196, v104, v105
	v_cvt_pk_bf16_f32 v197, v106, v107
	v_mul_f32_e32 v246, v105, v105
	v_mul_f32_e32 v247, v107, v107
	global_store_dwordx2 v245, v[196:197], s[22:23] offset:32
	v_fmac_f32_e32 v246, v104, v104
	v_fmac_f32_e32 v247, v106, v106
	v_add_f32_e32 v246, v246, v247
	v_add_f32_e32 v181, v246, v181
	v_cvt_pk_bf16_f32 v194, v100, v101
	v_cvt_pk_bf16_f32 v195, v102, v103
	v_mul_f32_e32 v246, v101, v101
	v_mul_f32_e32 v247, v103, v103
	global_store_dwordx2 v245, v[194:195], s[22:23] offset:256
	v_fmac_f32_e32 v246, v100, v100
	v_fmac_f32_e32 v247, v102, v102
	v_add_f32_e32 v246, v246, v247
	v_add_f32_e32 v181, v246, v181
	v_cvt_pk_bf16_f32 v196, v92, v93
	v_cvt_pk_bf16_f32 v197, v94, v95
	v_mul_f32_e32 v246, v93, v93
	v_mul_f32_e32 v247, v95, v95
	global_store_dwordx2 v245, v[196:197], s[22:23] offset:288
	v_fmac_f32_e32 v246, v92, v92
	v_fmac_f32_e32 v247, v94, v94
	v_add_f32_e32 v246, v246, v247
	v_add_f32_e32 v181, v246, v181
	s_waitcnt vmcnt(28)
; __device__ __forceinline__ unsigned cvt_pk_bf16(float lo, float hi) { unsigned r; asm volatile("v_cvt_pk_bf16_f32 %0, %1, %2" : "=v"(r) : "v"(lo), "v"(hi)); return r; }
;     __device__ __forceinline__ void operator()(const f32x4 (&acc)[2][2][4][2], const Unit& u, int wr, int wc, int fr, int fq) const {
;     ...
;         for (int gi = 0; gi < 8; ++gi) {
;             const int ai = gi >> 2, m = gi & 3;
;             const int row = row0 + ai * HALF + m * 16;
;             const size_t off = (size_t)row * ldc + col0;
;             if (gi + 1 < 8) {
;                 const size_t offn = (size_t)(row0 + ((gi + 1) >> 2) * HALF + ((gi + 1) & 3) * 16) * ldc + col0;
; #pragma unroll
;                 for (int q = 0; q < 4; ++q) bs[(gi + 1) & 1][q] = *(const f32x4*)(xin + offn + (q >> 1) * HALF + (q & 1) * 16);
;             }
;             float sq = 0.f;
; #pragma unroll
;             for (int q = 0; q < 4; ++q) {
;                 const int bj = q >> 1, n = q & 1;
;                 const f32x4 o = bs[gi & 1][q] + acc[ai][bj][m][n];
;                 *(f32x4*)(out + off + bj * HALF + n * 16) = o;
;                 if (ss) {
;                     u32x2 w; w.x = cvt_pk_bf16(o[0], o[1]); w.y = cvt_pk_bf16(o[2], o[3]);
;                     *(u32x2*)(xb + off + bj * HALF + n * 16) = w;
;                     sq += (o[0] * o[0] + o[1] * o[1]) + (o[2] * o[2] + o[3] * o[3]);
;                 }
;             }
;             if (ss) { sq += __shfl_xor(sq, 16); sq += __shfl_xor(sq, 32); if (fq == 0) ss[(size_t)row * 32 + u.pn * 4 + wc] = sq; }
	v_pk_add_f32 v[96:97], v[206:207], v[96:97]
	v_pk_add_f32 v[98:99], v[208:209], v[98:99]
	v_pk_add_f32 v[88:89], v[210:211], v[88:89]
	v_pk_add_f32 v[90:91], v[212:213], v[90:91]
	v_pk_add_f32 v[84:85], v[214:215], v[84:85]
	v_pk_add_f32 v[86:87], v[216:217], v[86:87]
	v_pk_add_f32 v[76:77], v[218:219], v[76:77]
	v_pk_add_f32 v[78:79], v[220:221], v[78:79]
	global_load_dwordx4 v[206:209], v192, s[14:15]
	global_load_dwordx4 v[210:213], v192, s[14:15] offset:64
	global_load_dwordx4 v[214:217], v192, s[14:15] offset:512
	global_load_dwordx4 v[218:221], v192, s[14:15] offset:576
	global_store_dwordx4 v162, v[96:99], s[72:73]
	global_store_dwordx4 v162, v[88:91], s[72:73] offset:64
	global_store_dwordx4 v162, v[84:87], s[72:73] offset:512
	global_store_dwordx4 v162, v[76:79], s[72:73] offset:576
	v_lshrrev_b32_e32 v245, 1, v162
	v_cvt_pk_bf16_f32 v194, v96, v97
	v_cvt_pk_bf16_f32 v195, v98, v99
	v_mul_f32_e32 v246, v97, v97
	v_mul_f32_e32 v247, v99, v99
	global_store_dwordx2 v245, v[194:195], s[22:23]
	v_fmac_f32_e32 v246, v96, v96
	v_fmac_f32_e32 v247, v98, v98
	v_add_f32_e32 v182, v246, v247
	v_cvt_pk_bf16_f32 v196, v88, v89
	v_cvt_pk_bf16_f32 v197, v90, v91
	v_mul_f32_e32 v246, v89, v89
	v_mul_f32_e32 v247, v91, v91
	global_store_dwordx2 v245, v[196:197], s[22:23] offset:32
	v_fmac_f32_e32 v246, v88, v88
	v_fmac_f32_e32 v247, v90, v90
	v_add_f32_e32 v246, v246, v247
	v_add_f32_e32 v182, v246, v182
	v_cvt_pk_bf16_f32 v194, v84, v85
	v_cvt_pk_bf16_f32 v195, v86, v87
	v_mul_f32_e32 v246, v85, v85
	v_mul_f32_e32 v247, v87, v87
	global_store_dwordx2 v245, v[194:195], s[22:23] offset:256
	v_fmac_f32_e32 v246, v84, v84
	v_fmac_f32_e32 v247, v86, v86
	v_add_f32_e32 v246, v246, v247
	v_add_f32_e32 v182, v246, v182
	v_cvt_pk_bf16_f32 v196, v76, v77
	v_cvt_pk_bf16_f32 v197, v78, v79
	v_mul_f32_e32 v246, v77, v77
	v_mul_f32_e32 v247, v79, v79
	global_store_dwordx2 v245, v[196:197], s[22:23] offset:288
	v_fmac_f32_e32 v246, v76, v76
	v_fmac_f32_e32 v247, v78, v78
	v_add_f32_e32 v246, v246, v247
	v_add_f32_e32 v182, v246, v182
	s_waitcnt vmcnt(36)
	v_pk_add_f32 v[80:81], v[222:223], v[80:81]
	v_pk_add_f32 v[82:83], v[224:225], v[82:83]
	v_pk_add_f32 v[72:73], v[226:227], v[72:73]
	v_pk_add_f32 v[74:75], v[228:229], v[74:75]
	v_pk_add_f32 v[68:69], v[230:231], v[68:69]
	v_pk_add_f32 v[70:71], v[232:233], v[70:71]
	v_pk_add_f32 v[64:65], v[234:235], v[64:65]
	v_pk_add_f32 v[66:67], v[236:237], v[66:67]
	global_load_dwordx4 v[222:225], v193, s[14:15]
	global_load_dwordx4 v[226:229], v193, s[14:15] offset:64
	global_load_dwordx4 v[230:233], v193, s[14:15] offset:512
	global_load_dwordx4 v[234:237], v193, s[14:15] offset:576
	global_store_dwordx4 v163, v[80:83], s[72:73]
	global_store_dwordx4 v163, v[72:75], s[72:73] offset:64
	global_store_dwordx4 v163, v[68:71], s[72:73] offset:512
	global_store_dwordx4 v163, v[64:67], s[72:73] offset:576
	v_lshrrev_b32_e32 v245, 1, v163
	v_cvt_pk_bf16_f32 v194, v80, v81
	v_cvt_pk_bf16_f32 v195, v82, v83
	v_mul_f32_e32 v246, v81, v81
	v_mul_f32_e32 v247, v83, v83
	global_store_dwordx2 v245, v[194:195], s[22:23]
	v_fmac_f32_e32 v246, v80, v80
	v_fmac_f32_e32 v247, v82, v82
	v_add_f32_e32 v183, v246, v247
	v_cvt_pk_bf16_f32 v196, v72, v73
	v_cvt_pk_bf16_f32 v197, v74, v75
	v_mul_f32_e32 v246, v73, v73
	v_mul_f32_e32 v247, v75, v75
	global_store_dwordx2 v245, v[196:197], s[22:23] offset:32
	v_fmac_f32_e32 v246, v72, v72
	v_fmac_f32_e32 v247, v74, v74
	v_add_f32_e32 v246, v246, v247
	v_add_f32_e32 v183, v246, v183
	v_cvt_pk_bf16_f32 v194, v68, v69
	v_cvt_pk_bf16_f32 v195, v70, v71
	v_mul_f32_e32 v246, v69, v69
	v_mul_f32_e32 v247, v71, v71
	global_store_dwordx2 v245, v[194:195], s[22:23] offset:256
	v_fmac_f32_e32 v246, v68, v68
	v_fmac_f32_e32 v247, v70, v70
	v_add_f32_e32 v246, v246, v247
	v_add_f32_e32 v183, v246, v183
	v_cvt_pk_bf16_f32 v196, v64, v65
	v_cvt_pk_bf16_f32 v197, v66, v67
	v_mul_f32_e32 v246, v65, v65
	v_mul_f32_e32 v247, v67, v67
	global_store_dwordx2 v245, v[196:197], s[22:23] offset:288
	v_fmac_f32_e32 v246, v64, v64
	v_fmac_f32_e32 v247, v66, v66
	v_add_f32_e32 v246, v246, v247
	v_add_f32_e32 v183, v246, v183
	s_waitcnt vmcnt(44)
	v_pk_add_f32 v[60:61], v[128:129], v[60:61]
	v_pk_add_f32 v[62:63], v[130:131], v[62:63]
	v_pk_add_f32 v[56:57], v[132:133], v[56:57]
	v_pk_add_f32 v[58:59], v[134:135], v[58:59]
	v_pk_add_f32 v[52:53], v[136:137], v[52:53]
	v_pk_add_f32 v[54:55], v[138:139], v[54:55]
	v_pk_add_f32 v[44:45], v[140:141], v[44:45]
	v_pk_add_f32 v[46:47], v[142:143], v[46:47]
	global_store_dwordx4 v164, v[60:63], s[72:73]
	global_store_dwordx4 v164, v[56:59], s[72:73] offset:64
	global_store_dwordx4 v164, v[52:55], s[72:73] offset:512
	global_store_dwordx4 v164, v[44:47], s[72:73] offset:576
	v_lshrrev_b32_e32 v245, 1, v164
	v_cvt_pk_bf16_f32 v194, v60, v61
	v_cvt_pk_bf16_f32 v195, v62, v63
	v_mul_f32_e32 v246, v61, v61
	v_mul_f32_e32 v247, v63, v63
	global_store_dwordx2 v245, v[194:195], s[22:23]
	v_fmac_f32_e32 v246, v60, v60
	v_fmac_f32_e32 v247, v62, v62
	v_add_f32_e32 v184, v246, v247
	v_cvt_pk_bf16_f32 v196, v56, v57
	v_cvt_pk_bf16_f32 v197, v58, v59
	v_mul_f32_e32 v246, v57, v57
	v_mul_f32_e32 v247, v59, v59
	global_store_dwordx2 v245, v[196:197], s[22:23] offset:32
	v_fmac_f32_e32 v246, v56, v56
	v_fmac_f32_e32 v247, v58, v58
	v_add_f32_e32 v246, v246, v247
	v_add_f32_e32 v184, v246, v184
	v_cvt_pk_bf16_f32 v194, v52, v53
	v_cvt_pk_bf16_f32 v195, v54, v55
	v_mul_f32_e32 v246, v53, v53
	v_mul_f32_e32 v247, v55, v55
	global_store_dwordx2 v245, v[194:195], s[22:23] offset:256
	v_fmac_f32_e32 v246, v52, v52
	v_fmac_f32_e32 v247, v54, v54
	v_add_f32_e32 v246, v246, v247
	v_add_f32_e32 v184, v246, v184
	v_cvt_pk_bf16_f32 v196, v44, v45
	v_cvt_pk_bf16_f32 v197, v46, v47
	v_mul_f32_e32 v246, v45, v45
	v_mul_f32_e32 v247, v47, v47
	global_store_dwordx2 v245, v[196:197], s[22:23] offset:288
	v_fmac_f32_e32 v246, v44, v44
	v_fmac_f32_e32 v247, v46, v46
	v_add_f32_e32 v246, v246, v247
	v_add_f32_e32 v184, v246, v184
	s_waitcnt vmcnt(40)
; __device__ __forceinline__ unsigned cvt_pk_bf16(float lo, float hi) { unsigned r; asm volatile("v_cvt_pk_bf16_f32 %0, %1, %2" : "=v"(r) : "v"(lo), "v"(hi)); return r; }
;     __device__ __forceinline__ void operator()(const f32x4 (&acc)[2][2][4][2], const Unit& u, int wr, int wc, int fr, int fq) const {
;     ...
;             float sq = 0.f;
; #pragma unroll
;             for (int q = 0; q < 4; ++q) {
;                 const int bj = q >> 1, n = q & 1;
;                 const f32x4 o = bs[gi & 1][q] + acc[ai][bj][m][n];
;                 *(f32x4*)(out + off + bj * HALF + n * 16) = o;
;                 if (ss) {
;                     u32x2 w; w.x = cvt_pk_bf16(o[0], o[1]); w.y = cvt_pk_bf16(o[2], o[3]);
;                     *(u32x2*)(xb + off + bj * HALF + n * 16) = w;
;                     sq += (o[0] * o[0] + o[1] * o[1]) + (o[2] * o[2] + o[3] * o[3]);
;                 }
;             }
;             if (ss) { sq += __shfl_xor(sq, 16); sq += __shfl_xor(sq, 32); if (fq == 0) ss[(size_t)row * 32 + u.pn * 4 + wc] = sq; }
	v_pk_add_f32 v[48:49], v[144:145], v[48:49]
	v_pk_add_f32 v[50:51], v[146:147], v[50:51]
	v_pk_add_f32 v[40:41], v[148:149], v[40:41]
	v_pk_add_f32 v[42:43], v[150:151], v[42:43]
	v_pk_add_f32 v[36:37], v[152:153], v[36:37]
	v_pk_add_f32 v[38:39], v[154:155], v[38:39]
	v_pk_add_f32 v[28:29], v[156:157], v[28:29]
	v_pk_add_f32 v[30:31], v[158:159], v[30:31]
	global_store_dwordx4 v165, v[48:51], s[72:73]
	global_store_dwordx4 v165, v[40:43], s[72:73] offset:64
	global_store_dwordx4 v165, v[36:39], s[72:73] offset:512
	global_store_dwordx4 v165, v[28:31], s[72:73] offset:576
	v_lshrrev_b32_e32 v245, 1, v165
	v_cvt_pk_bf16_f32 v194, v48, v49
	v_cvt_pk_bf16_f32 v195, v50, v51
	v_mul_f32_e32 v246, v49, v49
	v_mul_f32_e32 v247, v51, v51
	global_store_dwordx2 v245, v[194:195], s[22:23]
	v_fmac_f32_e32 v246, v48, v48
	v_fmac_f32_e32 v247, v50, v50
	v_add_f32_e32 v185, v246, v247
	v_cvt_pk_bf16_f32 v196, v40, v41
	v_cvt_pk_bf16_f32 v197, v42, v43
	v_mul_f32_e32 v246, v41, v41
	v_mul_f32_e32 v247, v43, v43
	global_store_dwordx2 v245, v[196:197], s[22:23] offset:32
	v_fmac_f32_e32 v246, v40, v40
	v_fmac_f32_e32 v247, v42, v42
	v_add_f32_e32 v246, v246, v247
	v_add_f32_e32 v185, v246, v185
	v_cvt_pk_bf16_f32 v194, v36, v37
	v_cvt_pk_bf16_f32 v195, v38, v39
	v_mul_f32_e32 v246, v37, v37
	v_mul_f32_e32 v247, v39, v39
	global_store_dwordx2 v245, v[194:195], s[22:23] offset:256
	v_fmac_f32_e32 v246, v36, v36
	v_fmac_f32_e32 v247, v38, v38
	v_add_f32_e32 v246, v246, v247
	v_add_f32_e32 v185, v246, v185
	v_cvt_pk_bf16_f32 v196, v28, v29
	v_cvt_pk_bf16_f32 v197, v30, v31
	v_mul_f32_e32 v246, v29, v29
	v_mul_f32_e32 v247, v31, v31
	global_store_dwordx2 v245, v[196:197], s[22:23] offset:288
	v_fmac_f32_e32 v246, v28, v28
	v_fmac_f32_e32 v247, v30, v30
	v_add_f32_e32 v246, v246, v247
	v_add_f32_e32 v185, v246, v185
	s_waitcnt vmcnt(36)
	v_pk_add_f32 v[32:33], v[206:207], v[32:33]
	v_pk_add_f32 v[34:35], v[208:209], v[34:35]
	v_pk_add_f32 v[24:25], v[210:211], v[24:25]
	v_pk_add_f32 v[26:27], v[212:213], v[26:27]
	v_pk_add_f32 v[20:21], v[214:215], v[20:21]
	v_pk_add_f32 v[22:23], v[216:217], v[22:23]
	v_pk_add_f32 v[12:13], v[218:219], v[12:13]
	v_pk_add_f32 v[14:15], v[220:221], v[14:15]
	global_store_dwordx4 v192, v[32:35], s[72:73]
	global_store_dwordx4 v192, v[24:27], s[72:73] offset:64
	global_store_dwordx4 v192, v[20:23], s[72:73] offset:512
	global_store_dwordx4 v192, v[12:15], s[72:73] offset:576
	v_lshrrev_b32_e32 v245, 1, v192
	v_cvt_pk_bf16_f32 v194, v32, v33
	v_cvt_pk_bf16_f32 v195, v34, v35
	v_mul_f32_e32 v246, v33, v33
	v_mul_f32_e32 v247, v35, v35
	global_store_dwordx2 v245, v[194:195], s[22:23]
	v_fmac_f32_e32 v246, v32, v32
	v_fmac_f32_e32 v247, v34, v34
	v_add_f32_e32 v186, v246, v247
	v_cvt_pk_bf16_f32 v196, v24, v25
	v_cvt_pk_bf16_f32 v197, v26, v27
	v_mul_f32_e32 v246, v25, v25
	v_mul_f32_e32 v247, v27, v27
	global_store_dwordx2 v245, v[196:197], s[22:23] offset:32
	v_fmac_f32_e32 v246, v24, v24
	v_fmac_f32_e32 v247, v26, v26
	v_add_f32_e32 v246, v246, v247
	v_add_f32_e32 v186, v246, v186
	v_cvt_pk_bf16_f32 v194, v20, v21
	v_cvt_pk_bf16_f32 v195, v22, v23
	v_mul_f32_e32 v246, v21, v21
	v_mul_f32_e32 v247, v23, v23
	global_store_dwordx2 v245, v[194:195], s[22:23] offset:256
	v_fmac_f32_e32 v246, v20, v20
	v_fmac_f32_e32 v247, v22, v22
	v_add_f32_e32 v246, v246, v247
	v_add_f32_e32 v186, v246, v186
	v_cvt_pk_bf16_f32 v196, v12, v13
	v_cvt_pk_bf16_f32 v197, v14, v15
	v_mul_f32_e32 v246, v13, v13
	v_mul_f32_e32 v247, v15, v15
	global_store_dwordx2 v245, v[196:197], s[22:23] offset:288
	v_fmac_f32_e32 v246, v12, v12
	v_fmac_f32_e32 v247, v14, v14
	v_add_f32_e32 v246, v246, v247
	v_add_f32_e32 v186, v246, v186
	s_waitcnt vmcnt(32)
	v_pk_add_f32 v[16:17], v[222:223], v[16:17]
	v_pk_add_f32 v[18:19], v[224:225], v[18:19]
	v_pk_add_f32 v[8:9], v[226:227], v[8:9]
	v_pk_add_f32 v[10:11], v[228:229], v[10:11]
	v_pk_add_f32 v[4:5], v[230:231], v[4:5]
	v_pk_add_f32 v[6:7], v[232:233], v[6:7]
	v_pk_add_f32 v[0:1], v[234:235], v[0:1]
	v_pk_add_f32 v[2:3], v[236:237], v[2:3]
	global_store_dwordx4 v193, v[16:19], s[72:73]
	global_store_dwordx4 v193, v[8:11], s[72:73] offset:64
	global_store_dwordx4 v193, v[4:7], s[72:73] offset:512
	global_store_dwordx4 v193, v[0:3], s[72:73] offset:576
	v_lshrrev_b32_e32 v245, 1, v193
	v_cvt_pk_bf16_f32 v194, v16, v17
	v_cvt_pk_bf16_f32 v195, v18, v19
	v_mul_f32_e32 v246, v17, v17
	v_mul_f32_e32 v247, v19, v19
	global_store_dwordx2 v245, v[194:195], s[22:23]
	v_fmac_f32_e32 v246, v16, v16
	v_fmac_f32_e32 v247, v18, v18
	v_add_f32_e32 v187, v246, v247
	v_cvt_pk_bf16_f32 v196, v8, v9
	v_cvt_pk_bf16_f32 v197, v10, v11
	v_mul_f32_e32 v246, v9, v9
	v_mul_f32_e32 v247, v11, v11
	global_store_dwordx2 v245, v[196:197], s[22:23] offset:32
	v_fmac_f32_e32 v246, v8, v8
	v_fmac_f32_e32 v247, v10, v10
	v_add_f32_e32 v246, v246, v247
	v_add_f32_e32 v187, v246, v187
	v_cvt_pk_bf16_f32 v194, v4, v5
	v_cvt_pk_bf16_f32 v195, v6, v7
	v_mul_f32_e32 v246, v5, v5
	v_mul_f32_e32 v247, v7, v7
	global_store_dwordx2 v245, v[194:195], s[22:23] offset:256
	v_fmac_f32_e32 v246, v4, v4
	v_fmac_f32_e32 v247, v6, v6
	v_add_f32_e32 v246, v246, v247
	v_add_f32_e32 v187, v246, v187
	v_cvt_pk_bf16_f32 v196, v0, v1
	v_cvt_pk_bf16_f32 v197, v2, v3
	v_mul_f32_e32 v246, v1, v1
	v_mul_f32_e32 v247, v3, v3
	global_store_dwordx2 v245, v[196:197], s[22:23] offset:288
	v_fmac_f32_e32 v246, v0, v0
	v_fmac_f32_e32 v247, v2, v2
	v_add_f32_e32 v246, v246, v247
	v_add_f32_e32 v187, v246, v187
	v_xor_b32_e32 v246, 16, v167
	v_xor_b32_e32 v247, 32, v167
	v_lshlrev_b32_e32 v246, 2, v246
	v_lshlrev_b32_e32 v247, 2, v247
	ds_bpermute_b32 v128, v246, v180
	ds_bpermute_b32 v129, v246, v181
	ds_bpermute_b32 v130, v246, v182
	ds_bpermute_b32 v131, v246, v183
	ds_bpermute_b32 v132, v246, v184
	ds_bpermute_b32 v133, v246, v185
	ds_bpermute_b32 v134, v246, v186
	ds_bpermute_b32 v135, v246, v187
	s_waitcnt lgkmcnt(0)
; __device__ __forceinline__ unsigned cvt_pk_bf16(float lo, float hi) { unsigned r; asm volatile("v_cvt_pk_bf16_f32 %0, %1, %2" : "=v"(r) : "v"(lo), "v"(hi)); return r; }
;     __device__ __forceinline__ void operator()(const f32x4 (&acc)[2][2][4][2], const Unit& u, int wr, int wc, int fr, int fq) const {
;     ...
;         for (int gi = 0; gi < 8; ++gi) {
;             const int ai = gi >> 2, m = gi & 3;
;             const int row = row0 + ai * HALF + m * 16;
;             const size_t off = (size_t)row * ldc + col0;
;             if (gi + 1 < 8) {
;                 const size_t offn = (size_t)(row0 + ((gi + 1) >> 2) * HALF + ((gi + 1) & 3) * 16) * ldc + col0;
; #pragma unroll
;                 for (int q = 0; q < 4; ++q) bs[(gi + 1) & 1][q] = *(const f32x4*)(xin + offn + (q >> 1) * HALF + (q & 1) * 16);
;             }
;             float sq = 0.f;
; #pragma unroll
;             for (int q = 0; q < 4; ++q) {
;                 const int bj = q >> 1, n = q & 1;
;                 const f32x4 o = bs[gi & 1][q] + acc[ai][bj][m][n];
;                 *(f32x4*)(out + off + bj * HALF + n * 16) = o;
;                 if (ss) {
;                     u32x2 w; w.x = cvt_pk_bf16(o[0], o[1]); w.y = cvt_pk_bf16(o[2], o[3]);
;                     *(u32x2*)(xb + off + bj * HALF + n * 16) = w;
;                     sq += (o[0] * o[0] + o[1] * o[1]) + (o[2] * o[2] + o[3] * o[3]);
;                 }
;             }
;             if (ss) { sq += __shfl_xor(sq, 16); sq += __shfl_xor(sq, 32); if (fq == 0) ss[(size_t)row * 32 + u.pn * 4 + wc] = sq; }
	v_add_f32_e32 v180, v180, v128
	v_add_f32_e32 v181, v181, v129
	v_add_f32_e32 v182, v182, v130
	v_add_f32_e32 v183, v183, v131
	v_add_f32_e32 v184, v184, v132
	v_add_f32_e32 v185, v185, v133
	v_add_f32_e32 v186, v186, v134
	v_add_f32_e32 v187, v187, v135
	ds_bpermute_b32 v128, v247, v180
	ds_bpermute_b32 v129, v247, v181
	ds_bpermute_b32 v130, v247, v182
	ds_bpermute_b32 v131, v247, v183
	ds_bpermute_b32 v132, v247, v184
	ds_bpermute_b32 v133, v247, v185
	ds_bpermute_b32 v134, v247, v186
	ds_bpermute_b32 v135, v247, v187
	s_waitcnt lgkmcnt(0)
	v_add_f32_e32 v180, v180, v128
	v_add_f32_e32 v181, v181, v129
	v_add_f32_e32 v182, v182, v130
	v_add_f32_e32 v183, v183, v131
	v_add_f32_e32 v184, v184, v132
	v_add_f32_e32 v185, v185, v133
	v_add_f32_e32 v186, v186, v134
	v_add_f32_e32 v187, v187, v135
	v_add_u32_e32 v136, 0x0, v189
	v_add_u32_e32 v137, 0x800, v189
	v_add_u32_e32 v138, 0x1000, v189
	v_add_u32_e32 v139, 0x1800, v189
	v_add_u32_e32 v140, 0x4000, v189
	v_add_u32_e32 v141, 0x4800, v189
	v_add_u32_e32 v142, 0x5000, v189
	v_add_u32_e32 v143, 0x5800, v189
	s_and_saveexec_b64 s[36:37], s[0:1]
	global_store_dword v136, v180, s[10:11]
	global_store_dword v137, v181, s[10:11]
	global_store_dword v138, v182, s[10:11]
	global_store_dword v139, v183, s[10:11]
	global_store_dword v140, v184, s[10:11]
	global_store_dword v141, v185, s[10:11]
	global_store_dword v142, v186, s[10:11]
	global_store_dword v143, v187, s[10:11]
	s_or_b64 exec, exec, s[36:37]
	s_branch .LBB0_385
.Lres_noss:
	v_lshl_add_u32 v246, s55, 8, v188
	v_lshl_or_b32 v247, s2, 8, v190
	v_lshlrev_b32_e32 v247, 2, v247
	v_lshl_add_u32 v160, v246, 13, v247
	v_add_u32_e32 v161, 0x20000, v160
	v_add_u32_e32 v162, 0x40000, v160
	v_add_u32_e32 v163, 0x60000, v160
	v_add_u32_e32 v164, 0x100000, v160
	v_add_u32_e32 v165, 0x120000, v160
	v_add_u32_e32 v192, 0x140000, v160
	v_add_u32_e32 v193, 0x160000, v160
	global_load_dwordx4 v[128:131], v160, s[14:15]
	global_load_dwordx4 v[132:135], v160, s[14:15] offset:64
	global_load_dwordx4 v[136:139], v160, s[14:15] offset:512
	global_load_dwordx4 v[140:143], v160, s[14:15] offset:576
	global_load_dwordx4 v[144:147], v161, s[14:15]
	global_load_dwordx4 v[148:151], v161, s[14:15] offset:64
	global_load_dwordx4 v[152:155], v161, s[14:15] offset:512
	global_load_dwordx4 v[156:159], v161, s[14:15] offset:576
	global_load_dwordx4 v[206:209], v162, s[14:15]
	global_load_dwordx4 v[210:213], v162, s[14:15] offset:64
	global_load_dwordx4 v[214:217], v162, s[14:15] offset:512
	global_load_dwordx4 v[218:221], v162, s[14:15] offset:576
	global_load_dwordx4 v[222:225], v163, s[14:15]
	global_load_dwordx4 v[226:229], v163, s[14:15] offset:64
	global_load_dwordx4 v[230:233], v163, s[14:15] offset:512
	global_load_dwordx4 v[234:237], v163, s[14:15] offset:576
	s_waitcnt vmcnt(12)
	v_pk_add_f32 v[124:125], v[128:129], v[124:125]
	v_pk_add_f32 v[126:127], v[130:131], v[126:127]
	v_pk_add_f32 v[120:121], v[132:133], v[120:121]
	v_pk_add_f32 v[122:123], v[134:135], v[122:123]
	v_pk_add_f32 v[116:117], v[136:137], v[116:117]
	v_pk_add_f32 v[118:119], v[138:139], v[118:119]
	v_pk_add_f32 v[108:109], v[140:141], v[108:109]
	v_pk_add_f32 v[110:111], v[142:143], v[110:111]
	global_load_dwordx4 v[128:131], v164, s[14:15]
	global_load_dwordx4 v[132:135], v164, s[14:15] offset:64
	global_load_dwordx4 v[136:139], v164, s[14:15] offset:512
	global_load_dwordx4 v[140:143], v164, s[14:15] offset:576
	global_store_dwordx4 v160, v[124:127], s[72:73]
	global_store_dwordx4 v160, v[120:123], s[72:73] offset:64
	global_store_dwordx4 v160, v[116:119], s[72:73] offset:512
	global_store_dwordx4 v160, v[108:111], s[72:73] offset:576
	s_waitcnt vmcnt(16)
	v_pk_add_f32 v[112:113], v[144:145], v[112:113]
	v_pk_add_f32 v[114:115], v[146:147], v[114:115]
	v_pk_add_f32 v[104:105], v[148:149], v[104:105]
	v_pk_add_f32 v[106:107], v[150:151], v[106:107]
	v_pk_add_f32 v[100:101], v[152:153], v[100:101]
	v_pk_add_f32 v[102:103], v[154:155], v[102:103]
	v_pk_add_f32 v[92:93], v[156:157], v[92:93]
	v_pk_add_f32 v[94:95], v[158:159], v[94:95]
	global_load_dwordx4 v[144:147], v165, s[14:15]
	global_load_dwordx4 v[148:151], v165, s[14:15] offset:64
	global_load_dwordx4 v[152:155], v165, s[14:15] offset:512
	global_load_dwordx4 v[156:159], v165, s[14:15] offset:576
	global_store_dwordx4 v161, v[112:115], s[72:73]
	global_store_dwordx4 v161, v[104:107], s[72:73] offset:64
	global_store_dwordx4 v161, v[100:103], s[72:73] offset:512
	global_store_dwordx4 v161, v[92:95], s[72:73] offset:576
	s_waitcnt vmcnt(20)
; #define PG8_BAR __builtin_amdgcn_s_barrier()
;     __device__ __forceinline__ void operator()(const f32x4 (&acc)[2][2][4][2], const Unit& u, int wr, int wc, int fr, int fq) const {
;     ...
;             if (gi + 1 < 8) {
;                 const size_t offn = (size_t)(row0 + ((gi + 1) >> 2) * HALF + ((gi + 1) & 3) * 16) * ldc + col0;
; #pragma unroll
;                 for (int q = 0; q < 4; ++q) bs[(gi + 1) & 1][q] = *(const f32x4*)(xin + offn + (q >> 1) * HALF + (q & 1) * 16);
;             }
;             float sq = 0.f;
; #pragma unroll
;             for (int q = 0; q < 4; ++q) {
;                 const int bj = q >> 1, n = q & 1;
;                 const f32x4 o = bs[gi & 1][q] + acc[ai][bj][m][n];
;                 *(f32x4*)(out + off + bj * HALF + n * 16) = o;
; template <class Epi>
; __device__ __forceinline__ void gemm_phase(LAS unsigned char* lds, const Gemm g, const StaticOrder& S, const Epi& E) {
;     ...
;         if (wr == 0) PG8_BAR;
;         E(acc, cur, wr, wc, fr, fq);
;         if (!has_next) break;
; #pragma unroll
;         for (int a = 0; a < 2; ++a)
; #pragma unroll
;             for (int b = 0; b < 2; ++b)
; #pragma unroll
;                 for (int m = 0; m < 4; ++m)
; #pragma unroll
;                     for (int n = 0; n < 2; ++n) acc[a][b][m][n] = (f32x4){0.f, 0.f, 0.f, 0.f};
;         cur = nxt; cA = nA; cB = nB; ++ui;
;         if (wr == 1) PG8_BAR;
	v_pk_add_f32 v[96:97], v[206:207], v[96:97]
	v_pk_add_f32 v[98:99], v[208:209], v[98:99]
	v_pk_add_f32 v[88:89], v[210:211], v[88:89]
	v_pk_add_f32 v[90:91], v[212:213], v[90:91]
	v_pk_add_f32 v[84:85], v[214:215], v[84:85]
	v_pk_add_f32 v[86:87], v[216:217], v[86:87]
	v_pk_add_f32 v[76:77], v[218:219], v[76:77]
	v_pk_add_f32 v[78:79], v[220:221], v[78:79]
	global_load_dwordx4 v[206:209], v192, s[14:15]
	global_load_dwordx4 v[210:213], v192, s[14:15] offset:64
	global_load_dwordx4 v[214:217], v192, s[14:15] offset:512
	global_load_dwordx4 v[218:221], v192, s[14:15] offset:576
	global_store_dwordx4 v162, v[96:99], s[72:73]
	global_store_dwordx4 v162, v[88:91], s[72:73] offset:64
	global_store_dwordx4 v162, v[84:87], s[72:73] offset:512
	global_store_dwordx4 v162, v[76:79], s[72:73] offset:576
	s_waitcnt vmcnt(24)
	v_pk_add_f32 v[80:81], v[222:223], v[80:81]
	v_pk_add_f32 v[82:83], v[224:225], v[82:83]
	v_pk_add_f32 v[72:73], v[226:227], v[72:73]
	v_pk_add_f32 v[74:75], v[228:229], v[74:75]
	v_pk_add_f32 v[68:69], v[230:231], v[68:69]
	v_pk_add_f32 v[70:71], v[232:233], v[70:71]
	v_pk_add_f32 v[64:65], v[234:235], v[64:65]
	v_pk_add_f32 v[66:67], v[236:237], v[66:67]
	global_load_dwordx4 v[222:225], v193, s[14:15]
	global_load_dwordx4 v[226:229], v193, s[14:15] offset:64
	global_load_dwordx4 v[230:233], v193, s[14:15] offset:512
	global_load_dwordx4 v[234:237], v193, s[14:15] offset:576
	global_store_dwordx4 v163, v[80:83], s[72:73]
	global_store_dwordx4 v163, v[72:75], s[72:73] offset:64
	global_store_dwordx4 v163, v[68:71], s[72:73] offset:512
	global_store_dwordx4 v163, v[64:67], s[72:73] offset:576
	s_waitcnt vmcnt(28)
	v_pk_add_f32 v[60:61], v[128:129], v[60:61]
	v_pk_add_f32 v[62:63], v[130:131], v[62:63]
	v_pk_add_f32 v[56:57], v[132:133], v[56:57]
	v_pk_add_f32 v[58:59], v[134:135], v[58:59]
	v_pk_add_f32 v[52:53], v[136:137], v[52:53]
	v_pk_add_f32 v[54:55], v[138:139], v[54:55]
	v_pk_add_f32 v[44:45], v[140:141], v[44:45]
	v_pk_add_f32 v[46:47], v[142:143], v[46:47]
	global_store_dwordx4 v164, v[60:63], s[72:73]
	global_store_dwordx4 v164, v[56:59], s[72:73] offset:64
	global_store_dwordx4 v164, v[52:55], s[72:73] offset:512
	global_store_dwordx4 v164, v[44:47], s[72:73] offset:576
	s_waitcnt vmcnt(24)
	v_pk_add_f32 v[48:49], v[144:145], v[48:49]
	v_pk_add_f32 v[50:51], v[146:147], v[50:51]
	v_pk_add_f32 v[40:41], v[148:149], v[40:41]
	v_pk_add_f32 v[42:43], v[150:151], v[42:43]
	v_pk_add_f32 v[36:37], v[152:153], v[36:37]
	v_pk_add_f32 v[38:39], v[154:155], v[38:39]
	v_pk_add_f32 v[28:29], v[156:157], v[28:29]
	v_pk_add_f32 v[30:31], v[158:159], v[30:31]
	global_store_dwordx4 v165, v[48:51], s[72:73]
	global_store_dwordx4 v165, v[40:43], s[72:73] offset:64
	global_store_dwordx4 v165, v[36:39], s[72:73] offset:512
	global_store_dwordx4 v165, v[28:31], s[72:73] offset:576
	s_waitcnt vmcnt(20)
	v_pk_add_f32 v[32:33], v[206:207], v[32:33]
	v_pk_add_f32 v[34:35], v[208:209], v[34:35]
	v_pk_add_f32 v[24:25], v[210:211], v[24:25]
	v_pk_add_f32 v[26:27], v[212:213], v[26:27]
	v_pk_add_f32 v[20:21], v[214:215], v[20:21]
	v_pk_add_f32 v[22:23], v[216:217], v[22:23]
	v_pk_add_f32 v[12:13], v[218:219], v[12:13]
	v_pk_add_f32 v[14:15], v[220:221], v[14:15]
	global_store_dwordx4 v192, v[32:35], s[72:73]
	global_store_dwordx4 v192, v[24:27], s[72:73] offset:64
	global_store_dwordx4 v192, v[20:23], s[72:73] offset:512
	global_store_dwordx4 v192, v[12:15], s[72:73] offset:576
	s_waitcnt vmcnt(16)
	v_pk_add_f32 v[16:17], v[222:223], v[16:17]
	v_pk_add_f32 v[18:19], v[224:225], v[18:19]
	v_pk_add_f32 v[8:9], v[226:227], v[8:9]
	v_pk_add_f32 v[10:11], v[228:229], v[10:11]
	v_pk_add_f32 v[4:5], v[230:231], v[4:5]
	v_pk_add_f32 v[6:7], v[232:233], v[6:7]
	v_pk_add_f32 v[0:1], v[234:235], v[0:1]
	v_pk_add_f32 v[2:3], v[236:237], v[2:3]
	global_store_dwordx4 v193, v[16:19], s[72:73]
	global_store_dwordx4 v193, v[8:11], s[72:73] offset:64
	global_store_dwordx4 v193, v[4:7], s[72:73] offset:512
	global_store_dwordx4 v193, v[0:3], s[72:73] offset:576
.LBB0_385:
	s_and_b64 vcc, exec, s[6:7]
	s_mov_b64 s[4:5], -1
	s_cbranch_vccnz .LBB0_330
	s_andn2_b64 vcc, exec, s[20:21]
	s_cbranch_vccnz .LBB0_329
	s_barrier
	s_branch .LBB0_329
.LBB0_396:
	s_waitcnt vmcnt(0)
	s_barrier
